# conv pass: staging loads and the tap-weight loads of an item all in flight together; LDS stores of the window after one counted wait
# baseline (speedup 1.0000x reference)
.LBB0_930:
	global_load_dword v133, v[94:95], off
	global_load_dword v132, v[96:97], off
	global_load_dword v131, v[98:99], off
	global_load_dword v130, v[100:101], off
	global_load_dword v128, v[102:103], off
	global_load_dword v126, v[104:105], off
	global_load_dword v135, v[38:39], off
	global_load_dword v134, v[38:39], off offset:2048
	global_load_dword v129, v[40:41], off
	global_load_dword v127, v[42:43], off
	global_load_dword v125, v[44:45], off
	global_load_dword v124, v[46:47], off
	global_load_dword v123, v[48:49], off
	global_load_dword v122, v[50:51], off
	global_load_dword v121, v[52:53], off
	global_load_dword v16, v[54:55], off
	global_load_dword v15, v[56:57], off
	global_load_dword v14, v[58:59], off
	global_load_dword v13, v[60:61], off
	global_load_dword v12, v[62:63], off
	global_load_dword v11, v[64:65], off
	global_load_dword v10, v[66:67], off
	global_load_dword v9, v[68:69], off
	global_load_dword v8, v[70:71], off
	global_load_dword v7, v[72:73], off
	global_load_dword v6, v[74:75], off
	global_load_dword v5, v[76:77], off
	global_load_dword v4, v[78:79], off
	global_load_dword v3, v[80:81], off
	global_load_dword v2, v[82:83], off
	global_load_dword v0, v[84:85], off
	global_load_dword v1, v[86:87], off
	s_cmp_lg_u32 s13, 32
	s_cbranch_scc1 .Lmy_cvs_skip
	s_waitcnt vmcnt(32)
	s_and_saveexec_b64 s[0:1], s[2:3]
	v_add_u32_e32 v236, v106, v107
	ds_write_b128 v236, v[204:207]
	s_or_b64 exec, exec, s[0:1]
	s_and_saveexec_b64 s[0:1], s[8:9]
	v_add_u32_e32 v236, v106, v108
	ds_write_b128 v236, v[208:211]
	s_or_b64 exec, exec, s[0:1]
	s_and_saveexec_b64 s[0:1], s[14:15]
	v_add_u32_e32 v236, v106, v109
	ds_write_b128 v236, v[212:215]
	s_or_b64 exec, exec, s[0:1]
	s_and_saveexec_b64 s[0:1], s[20:21]
	v_add_u32_e32 v236, v106, v110
	ds_write_b128 v236, v[216:219]
	s_or_b64 exec, exec, s[0:1]
	s_and_saveexec_b64 s[0:1], s[26:27]
	v_add_u32_e32 v236, v106, v111
	ds_write_b128 v236, v[220:223]
	s_or_b64 exec, exec, s[0:1]
	s_and_saveexec_b64 s[0:1], s[34:35]
	v_add_u32_e32 v236, v106, v112
	ds_write_b128 v236, v[224:227]
	s_or_b64 exec, exec, s[0:1]
	s_and_saveexec_b64 s[0:1], s[36:37]
	v_add_u32_e32 v236, v106, v113
	ds_write_b128 v236, v[228:231]
	s_or_b64 exec, exec, s[0:1]
	s_and_saveexec_b64 s[0:1], s[38:39]
	v_add_u32_e32 v236, v106, v114
	ds_write_b128 v236, v[232:235]
	s_or_b64 exec, exec, s[0:1]
.Lmy_cvs_skip:
	s_waitcnt vmcnt(0) lgkmcnt(0)
	s_barrier
	ds_read_u16 v136, v115
	ds_read_u16 v137, v115 offset:1024
	ds_read_u16 v138, v115 offset:57344
	ds_read_u16 v139, v115 offset:58368
	ds_read_u16 v191, v115 offset:59392
	ds_read_u16 v192, v115 offset:60416
	ds_read_u16 v193, v115 offset:61440
	ds_read_u16 v194, v115 offset:62464
	s_waitcnt lgkmcnt(7)
	v_lshlrev_b32_e32 v195, 16, v136
	s_waitcnt lgkmcnt(6)
	v_lshlrev_b32_e32 v196, 16, v137
	ds_read_u16 v136, v115 offset:2048
	ds_read_u16 v137, v115 offset:3072
	ds_read_u16 v140, v115 offset:4096
	ds_read_u16 v141, v115 offset:5120
	ds_read_u16 v142, v115 offset:6144
	ds_read_u16 v143, v115 offset:7168
	ds_read_u16 v144, v115 offset:8192
	ds_read_u16 v145, v115 offset:9216
	s_waitcnt lgkmcnt(7)
	v_lshlrev_b32_e32 v197, 16, v136
	s_waitcnt lgkmcnt(6)
	v_lshlrev_b32_e32 v198, 16, v137
	s_waitcnt lgkmcnt(5)
	v_lshlrev_b32_e32 v199, 16, v140
	s_waitcnt lgkmcnt(4)
	v_lshlrev_b32_e32 v200, 16, v141
	s_waitcnt lgkmcnt(3)
	v_lshlrev_b32_e32 v201, 16, v142
	s_waitcnt lgkmcnt(2)
	v_lshlrev_b32_e32 v190, 16, v143
	s_waitcnt lgkmcnt(1)
	v_lshlrev_b32_e32 v189, 16, v144
	s_waitcnt lgkmcnt(0)
	v_lshlrev_b32_e32 v188, 16, v145
	ds_read_u16 v136, v115 offset:10240
	ds_read_u16 v137, v115 offset:11264
	ds_read_u16 v140, v115 offset:12288
	ds_read_u16 v141, v115 offset:13312
	ds_read_u16 v142, v115 offset:14336
	ds_read_u16 v143, v115 offset:15360
	ds_read_u16 v144, v115 offset:16384
	ds_read_u16 v145, v115 offset:17408
	s_waitcnt lgkmcnt(7)
	v_lshlrev_b32_e32 v187, 16, v136
	s_waitcnt lgkmcnt(6)
	v_lshlrev_b32_e32 v186, 16, v137
	s_waitcnt lgkmcnt(5)
	v_lshlrev_b32_e32 v185, 16, v140
	s_waitcnt lgkmcnt(4)
	v_lshlrev_b32_e32 v184, 16, v141
	s_waitcnt lgkmcnt(3)
	v_lshlrev_b32_e32 v183, 16, v142
	s_waitcnt lgkmcnt(2)
	v_lshlrev_b32_e32 v182, 16, v143
	s_waitcnt lgkmcnt(1)
	v_lshlrev_b32_e32 v181, 16, v144
	s_waitcnt lgkmcnt(0)
	v_lshlrev_b32_e32 v180, 16, v145
	ds_read_u16 v136, v115 offset:18432
	ds_read_u16 v137, v115 offset:19456
	ds_read_u16 v140, v115 offset:20480
	ds_read_u16 v141, v115 offset:21504
	ds_read_u16 v142, v115 offset:22528
	ds_read_u16 v143, v115 offset:23552
	ds_read_u16 v144, v115 offset:24576
	ds_read_u16 v145, v115 offset:25600
	s_waitcnt lgkmcnt(7)
	v_lshlrev_b32_e32 v179, 16, v136
	s_waitcnt lgkmcnt(6)
	v_lshlrev_b32_e32 v178, 16, v137
	s_waitcnt lgkmcnt(5)
	v_lshlrev_b32_e32 v177, 16, v140
	s_waitcnt lgkmcnt(4)
	v_lshlrev_b32_e32 v176, 16, v141
	s_waitcnt lgkmcnt(3)
	v_lshlrev_b32_e32 v175, 16, v142
	s_waitcnt lgkmcnt(2)
	v_lshlrev_b32_e32 v174, 16, v143
	ds_read_u16 v136, v115 offset:26624
	ds_read_u16 v137, v115 offset:27648
	ds_read_u16 v140, v115 offset:28672
	ds_read_u16 v141, v115 offset:29696
	ds_read_u16 v142, v115 offset:30720
	ds_read_u16 v143, v115 offset:31744
	s_waitcnt lgkmcnt(7)
	v_lshlrev_b32_e32 v173, 16, v144
	s_waitcnt lgkmcnt(6)
	v_lshlrev_b32_e32 v172, 16, v145
	s_waitcnt lgkmcnt(5)
	v_lshlrev_b32_e32 v171, 16, v136
	s_waitcnt lgkmcnt(4)
	v_lshlrev_b32_e32 v170, 16, v137
	s_waitcnt lgkmcnt(3)
	v_lshlrev_b32_e32 v169, 16, v140
	s_waitcnt lgkmcnt(2)
	v_lshlrev_b32_e32 v168, 16, v141
	s_waitcnt lgkmcnt(1)
	v_lshlrev_b32_e32 v167, 16, v142
	s_waitcnt lgkmcnt(0)
	v_lshlrev_b32_e32 v142, 16, v143
	ds_read_u16 v136, v115 offset:32768
	ds_read_u16 v137, v115 offset:33792
	ds_read_u16 v140, v115 offset:34816
	ds_read_u16 v141, v115 offset:35840
	ds_read_u16 v143, v115 offset:36864
	ds_read_u16 v144, v115 offset:37888
	ds_read_u16 v145, v115 offset:38912
	ds_read_u16 v147, v115 offset:39936
	s_waitcnt lgkmcnt(7)
	v_lshlrev_b32_e32 v164, 16, v136
	s_waitcnt lgkmcnt(6)
	v_lshlrev_b32_e32 v161, 16, v137
	s_waitcnt lgkmcnt(5)
	v_lshlrev_b32_e32 v158, 16, v140
	s_waitcnt lgkmcnt(4)
	v_lshlrev_b32_e32 v155, 16, v141
	s_waitcnt lgkmcnt(3)
	v_lshlrev_b32_e32 v152, 16, v143
	s_waitcnt lgkmcnt(2)
	v_lshlrev_b32_e32 v149, 16, v144
	s_waitcnt lgkmcnt(1)
	v_lshlrev_b32_e32 v146, 16, v145
	s_waitcnt lgkmcnt(0)
	v_lshlrev_b32_e32 v143, 16, v147
	ds_read_u16 v136, v115 offset:40960
	ds_read_u16 v137, v115 offset:41984
	ds_read_u16 v140, v115 offset:43008
	ds_read_u16 v141, v115 offset:44032
	ds_read_u16 v144, v115 offset:45056
	ds_read_u16 v145, v115 offset:46080
	ds_read_u16 v147, v115 offset:47104
	ds_read_u16 v148, v115 offset:48128
	s_waitcnt lgkmcnt(7)
	v_lshlrev_b32_e32 v165, 16, v136
	s_waitcnt lgkmcnt(6)
	v_lshlrev_b32_e32 v162, 16, v137
	s_waitcnt lgkmcnt(5)
	v_lshlrev_b32_e32 v159, 16, v140
	s_waitcnt lgkmcnt(4)
	v_lshlrev_b32_e32 v156, 16, v141
	s_waitcnt lgkmcnt(3)
	v_lshlrev_b32_e32 v153, 16, v144
	s_waitcnt lgkmcnt(2)
	v_lshlrev_b32_e32 v150, 16, v145
	s_waitcnt lgkmcnt(0)
	v_lshlrev_b32_e32 v144, 16, v148
	ds_read_u16 v136, v115 offset:49152
	ds_read_u16 v137, v115 offset:50176
	ds_read_u16 v140, v115 offset:51200
	ds_read_u16 v141, v115 offset:52224
	ds_read_u16 v145, v115 offset:53248
	ds_read_u16 v148, v115 offset:54272
	ds_read_u16 v202, v115 offset:55296
	ds_read_u16 v203, v115 offset:56320
	s_waitcnt lgkmcnt(5)
	v_lshlrev_b32_e32 v160, 16, v140
	s_waitcnt lgkmcnt(4)
	v_lshlrev_b32_e32 v157, 16, v141
	v_lshlrev_b32_e32 v141, 16, v138
	v_lshlrev_b32_e32 v140, 16, v139
	v_lshlrev_b32_e32 v139, 16, v191
	v_lshlrev_b32_e32 v138, 16, v192
	v_lshlrev_b32_e32 v147, 16, v147
	v_lshlrev_b32_e32 v166, 16, v136
	v_lshlrev_b32_e32 v163, 16, v137
	s_waitcnt lgkmcnt(3)
	v_lshlrev_b32_e32 v154, 16, v145
	s_waitcnt lgkmcnt(2)
	v_lshlrev_b32_e32 v151, 16, v148
	s_waitcnt lgkmcnt(1)
	v_lshlrev_b32_e32 v148, 16, v202
	s_waitcnt lgkmcnt(0)
	v_lshlrev_b32_e32 v145, 16, v203
	v_lshlrev_b32_e32 v137, 16, v193
	v_lshlrev_b32_e32 v136, 16, v194
	s_cmp_ge_u32 s60, s13
	v_fma_f32 v191, v135, v195, v1
	v_fma_f32 v192, v135, v196, v1
	v_fmac_f32_e32 v191, v134, v196
	v_fmac_f32_e32 v192, v134, v197
	v_fmac_f32_e32 v191, v133, v197
	v_fmac_f32_e32 v192, v133, v198
	v_fmac_f32_e32 v191, v132, v198
	v_fmac_f32_e32 v192, v132, v199
	v_fmac_f32_e32 v191, v131, v199
	v_fmac_f32_e32 v192, v131, v200
	v_fmac_f32_e32 v191, v130, v200
	v_fmac_f32_e32 v192, v130, v201
	v_fmac_f32_e32 v191, v128, v201
	v_fmac_f32_e32 v192, v128, v190
	v_fmac_f32_e32 v191, v126, v190
	v_fmac_f32_e32 v192, v126, v189
	v_fmac_f32_e32 v191, v129, v189
	v_fmac_f32_e32 v192, v129, v188
	v_fmac_f32_e32 v191, v127, v188
	v_fmac_f32_e32 v192, v127, v187
	v_fmac_f32_e32 v191, v125, v187
	v_fmac_f32_e32 v192, v125, v186
	v_fmac_f32_e32 v191, v124, v186
	v_fmac_f32_e32 v192, v124, v185
	v_fmac_f32_e32 v191, v123, v185
	v_fmac_f32_e32 v192, v123, v184
	v_fmac_f32_e32 v191, v122, v184
	v_fmac_f32_e32 v192, v122, v183
	v_fmac_f32_e32 v191, v121, v183
	v_fmac_f32_e32 v192, v121, v182
	v_fmac_f32_e32 v191, v16, v182
	v_fmac_f32_e32 v192, v16, v181
	v_fmac_f32_e32 v191, v15, v181
	v_fmac_f32_e32 v192, v15, v180
	v_fmac_f32_e32 v191, v14, v180
	v_fmac_f32_e32 v192, v14, v179
	v_fmac_f32_e32 v191, v13, v179
	v_fmac_f32_e32 v192, v13, v178
	v_fmac_f32_e32 v191, v12, v178
	v_fmac_f32_e32 v192, v12, v177
	v_fmac_f32_e32 v191, v11, v177
	v_fmac_f32_e32 v192, v11, v176
	v_fmac_f32_e32 v191, v10, v176
	v_fmac_f32_e32 v192, v10, v175
	v_fmac_f32_e32 v191, v9, v175
	v_fmac_f32_e32 v192, v9, v174
	v_fmac_f32_e32 v191, v8, v174
	v_fmac_f32_e32 v192, v8, v173
	v_fmac_f32_e32 v191, v7, v173
	v_fmac_f32_e32 v192, v7, v172
	v_fmac_f32_e32 v191, v6, v172
	v_fmac_f32_e32 v192, v6, v171
	v_fmac_f32_e32 v191, v5, v171
	v_fmac_f32_e32 v192, v5, v170
	v_fmac_f32_e32 v191, v4, v170
	v_fmac_f32_e32 v192, v4, v169
	v_fmac_f32_e32 v191, v3, v169
	v_fmac_f32_e32 v192, v3, v168
	v_fmac_f32_e32 v191, v2, v168
	v_fmac_f32_e32 v192, v2, v167
	v_fmac_f32_e32 v191, v0, v167
	v_fmac_f32_e32 v192, v0, v142
	ds_write2st64_b32 v116, v191, v192 offset1:8
	v_fma_f32 v191, v135, v197, v1
	v_fma_f32 v192, v135, v198, v1
	v_fmac_f32_e32 v191, v134, v198
	v_fmac_f32_e32 v192, v134, v199
	v_fmac_f32_e32 v191, v133, v199
	v_fmac_f32_e32 v192, v133, v200
	v_fmac_f32_e32 v191, v132, v200
	v_fmac_f32_e32 v192, v132, v201
	v_fmac_f32_e32 v191, v131, v201
	v_fmac_f32_e32 v192, v131, v190
	v_fmac_f32_e32 v191, v130, v190
	v_fmac_f32_e32 v192, v130, v189
	v_fmac_f32_e32 v191, v128, v189
	v_fmac_f32_e32 v192, v128, v188
	v_fmac_f32_e32 v191, v126, v188
	v_fmac_f32_e32 v192, v126, v187
	v_fmac_f32_e32 v191, v129, v187
	v_fmac_f32_e32 v192, v129, v186
	v_fmac_f32_e32 v191, v127, v186
	v_fmac_f32_e32 v192, v127, v185
	v_fmac_f32_e32 v191, v125, v185
	v_fmac_f32_e32 v192, v125, v184
	v_fmac_f32_e32 v191, v124, v184
	v_fmac_f32_e32 v192, v124, v183
	v_fmac_f32_e32 v191, v123, v183
	v_fmac_f32_e32 v192, v123, v182
	v_fmac_f32_e32 v191, v122, v182
	v_fmac_f32_e32 v192, v122, v181
	v_fmac_f32_e32 v191, v121, v181
	v_fmac_f32_e32 v192, v121, v180
	v_fmac_f32_e32 v191, v16, v180
	v_fmac_f32_e32 v192, v16, v179
	v_fmac_f32_e32 v191, v15, v179
	v_fmac_f32_e32 v192, v15, v178
	v_fmac_f32_e32 v191, v14, v178
	v_fmac_f32_e32 v192, v14, v177
	v_fmac_f32_e32 v191, v13, v177
	v_fmac_f32_e32 v192, v13, v176
	v_fmac_f32_e32 v191, v12, v176
	v_fmac_f32_e32 v192, v12, v175
	v_fmac_f32_e32 v191, v11, v175
	v_fmac_f32_e32 v192, v11, v174
	v_fmac_f32_e32 v191, v10, v174
	v_fmac_f32_e32 v192, v10, v173
	v_fmac_f32_e32 v191, v9, v173
	v_fmac_f32_e32 v192, v9, v172
	v_fmac_f32_e32 v191, v8, v172
	v_fmac_f32_e32 v192, v8, v171
	v_fmac_f32_e32 v191, v7, v171
	v_fmac_f32_e32 v192, v7, v170
	v_fmac_f32_e32 v191, v6, v170
	v_fmac_f32_e32 v192, v6, v169
	v_fmac_f32_e32 v191, v5, v169
	v_fmac_f32_e32 v192, v5, v168
	v_fmac_f32_e32 v191, v4, v168
	v_fmac_f32_e32 v192, v4, v167
	v_fmac_f32_e32 v191, v3, v167
	v_fmac_f32_e32 v192, v3, v142
	v_fmac_f32_e32 v191, v2, v142
	v_fmac_f32_e32 v192, v2, v164
	v_fmac_f32_e32 v191, v0, v164
	v_fmac_f32_e32 v192, v0, v161
	ds_write2st64_b32 v116, v191, v192 offset0:16 offset1:24
	s_cmp_eq_u32 s13, 4
	s_cbranch_scc1 .Lmy_conv_skip
	v_fma_f32 v191, v135, v199, v1
	v_fma_f32 v192, v135, v200, v1
	v_fmac_f32_e32 v191, v134, v200
	v_fmac_f32_e32 v192, v134, v201
	v_fmac_f32_e32 v191, v133, v201
	v_fmac_f32_e32 v192, v133, v190
	v_fmac_f32_e32 v191, v132, v190
	v_fmac_f32_e32 v192, v132, v189
	v_fmac_f32_e32 v191, v131, v189
	v_fmac_f32_e32 v192, v131, v188
	v_fmac_f32_e32 v191, v130, v188
	v_fmac_f32_e32 v192, v130, v187
	v_fmac_f32_e32 v191, v128, v187
	v_fmac_f32_e32 v192, v128, v186
	v_fmac_f32_e32 v191, v126, v186
	v_fmac_f32_e32 v192, v126, v185
	v_fmac_f32_e32 v191, v129, v185
	v_fmac_f32_e32 v192, v129, v184
	v_fmac_f32_e32 v191, v127, v184
	v_fmac_f32_e32 v192, v127, v183
	v_fmac_f32_e32 v191, v125, v183
	v_fmac_f32_e32 v192, v125, v182
	v_fmac_f32_e32 v191, v124, v182
	v_fmac_f32_e32 v192, v124, v181
	v_fmac_f32_e32 v191, v123, v181
	v_fmac_f32_e32 v192, v123, v180
	v_fmac_f32_e32 v191, v122, v180
	v_fmac_f32_e32 v192, v122, v179
	v_fmac_f32_e32 v191, v121, v179
	v_fmac_f32_e32 v192, v121, v178
	v_fmac_f32_e32 v191, v16, v178
	v_fmac_f32_e32 v192, v16, v177
	v_fmac_f32_e32 v191, v15, v177
	v_fmac_f32_e32 v192, v15, v176
	v_fmac_f32_e32 v191, v14, v176
	v_fmac_f32_e32 v192, v14, v175
	v_fmac_f32_e32 v191, v13, v175
	v_fmac_f32_e32 v192, v13, v174
	v_fmac_f32_e32 v191, v12, v174
	v_fmac_f32_e32 v192, v12, v173
	v_fmac_f32_e32 v191, v11, v173
	v_fmac_f32_e32 v192, v11, v172
	v_fmac_f32_e32 v191, v10, v172
	v_fmac_f32_e32 v192, v10, v171
	v_fmac_f32_e32 v191, v9, v171
	v_fmac_f32_e32 v192, v9, v170
	v_fmac_f32_e32 v191, v8, v170
	v_fmac_f32_e32 v192, v8, v169
	v_fmac_f32_e32 v191, v7, v169
	v_fmac_f32_e32 v192, v7, v168
	v_fmac_f32_e32 v191, v6, v168
	v_fmac_f32_e32 v192, v6, v167
	v_fmac_f32_e32 v191, v5, v167
	v_fmac_f32_e32 v192, v5, v142
	v_fmac_f32_e32 v191, v4, v142
	v_fmac_f32_e32 v192, v4, v164
	v_fmac_f32_e32 v191, v3, v164
	v_fmac_f32_e32 v192, v3, v161
	v_fmac_f32_e32 v191, v2, v161
	v_fmac_f32_e32 v192, v2, v158
	v_fmac_f32_e32 v191, v0, v158
	v_fmac_f32_e32 v192, v0, v155
	ds_write2st64_b32 v116, v191, v192 offset0:32 offset1:40
	v_fma_f32 v191, v135, v201, v1
	v_fmac_f32_e32 v191, v134, v190
	v_fma_f32 v190, v135, v190, v1
	v_fmac_f32_e32 v191, v133, v189
	v_fmac_f32_e32 v190, v134, v189
	v_fma_f32 v189, v135, v189, v1
	v_fmac_f32_e32 v191, v132, v188
	v_fmac_f32_e32 v190, v133, v188
	v_fmac_f32_e32 v189, v134, v188
	v_fma_f32 v188, v135, v188, v1
	v_fmac_f32_e32 v191, v131, v187
	v_fmac_f32_e32 v190, v132, v187
	v_fmac_f32_e32 v189, v133, v187
	v_fmac_f32_e32 v188, v134, v187
	v_fma_f32 v187, v135, v187, v1
	v_fmac_f32_e32 v191, v130, v186
	v_fmac_f32_e32 v190, v131, v186
	v_fmac_f32_e32 v189, v132, v186
	v_fmac_f32_e32 v188, v133, v186
	v_fmac_f32_e32 v187, v134, v186
	v_fma_f32 v186, v135, v186, v1
	v_fmac_f32_e32 v191, v128, v185
	v_fmac_f32_e32 v190, v130, v185
	v_fmac_f32_e32 v189, v131, v185
	v_fmac_f32_e32 v188, v132, v185
	v_fmac_f32_e32 v187, v133, v185
	v_fmac_f32_e32 v186, v134, v185
	v_fma_f32 v185, v135, v185, v1
	v_fmac_f32_e32 v191, v126, v184
	v_fmac_f32_e32 v190, v128, v184
	v_fmac_f32_e32 v189, v130, v184
	v_fmac_f32_e32 v188, v131, v184
	v_fmac_f32_e32 v187, v132, v184
	v_fmac_f32_e32 v186, v133, v184
	v_fmac_f32_e32 v185, v134, v184
	v_fma_f32 v184, v135, v184, v1
	v_fmac_f32_e32 v191, v129, v183
	v_fmac_f32_e32 v190, v126, v183
	v_fmac_f32_e32 v189, v128, v183
	v_fmac_f32_e32 v188, v130, v183
	v_fmac_f32_e32 v187, v131, v183
	v_fmac_f32_e32 v186, v132, v183
	v_fmac_f32_e32 v185, v133, v183
	v_fmac_f32_e32 v184, v134, v183
	v_fma_f32 v183, v135, v183, v1
	v_fmac_f32_e32 v191, v127, v182
	v_fmac_f32_e32 v190, v129, v182
	v_fmac_f32_e32 v189, v126, v182
	v_fmac_f32_e32 v188, v128, v182
	v_fmac_f32_e32 v187, v130, v182
	v_fmac_f32_e32 v186, v131, v182
	v_fmac_f32_e32 v185, v132, v182
	v_fmac_f32_e32 v184, v133, v182
	v_fmac_f32_e32 v183, v134, v182
	v_fma_f32 v182, v135, v182, v1
	v_fmac_f32_e32 v191, v125, v181
	v_fmac_f32_e32 v190, v127, v181
	v_fmac_f32_e32 v189, v129, v181
	v_fmac_f32_e32 v188, v126, v181
	v_fmac_f32_e32 v187, v128, v181
	v_fmac_f32_e32 v186, v130, v181
	v_fmac_f32_e32 v185, v131, v181
	v_fmac_f32_e32 v184, v132, v181
	v_fmac_f32_e32 v183, v133, v181
	v_fmac_f32_e32 v182, v134, v181
	v_fma_f32 v181, v135, v181, v1
	v_fmac_f32_e32 v191, v124, v180
	v_fmac_f32_e32 v190, v125, v180
	v_fmac_f32_e32 v189, v127, v180
	v_fmac_f32_e32 v188, v129, v180
	v_fmac_f32_e32 v187, v126, v180
	v_fmac_f32_e32 v186, v128, v180
	v_fmac_f32_e32 v185, v130, v180
	v_fmac_f32_e32 v184, v131, v180
	v_fmac_f32_e32 v183, v132, v180
	v_fmac_f32_e32 v182, v133, v180
	v_fmac_f32_e32 v181, v134, v180
	v_fma_f32 v180, v135, v180, v1
	v_fmac_f32_e32 v191, v123, v179
	v_fmac_f32_e32 v190, v124, v179
	v_fmac_f32_e32 v189, v125, v179
	v_fmac_f32_e32 v188, v127, v179
	v_fmac_f32_e32 v187, v129, v179
	v_fmac_f32_e32 v186, v126, v179
	v_fmac_f32_e32 v185, v128, v179
	v_fmac_f32_e32 v184, v130, v179
	v_fmac_f32_e32 v183, v131, v179
	v_fmac_f32_e32 v182, v132, v179
	v_fmac_f32_e32 v181, v133, v179
	v_fmac_f32_e32 v180, v134, v179
	v_fma_f32 v179, v135, v179, v1
	v_fmac_f32_e32 v191, v122, v178
	v_fmac_f32_e32 v190, v123, v178
	v_fmac_f32_e32 v189, v124, v178
	v_fmac_f32_e32 v188, v125, v178
	v_fmac_f32_e32 v187, v127, v178
	v_fmac_f32_e32 v186, v129, v178
	v_fmac_f32_e32 v185, v126, v178
	v_fmac_f32_e32 v184, v128, v178
	v_fmac_f32_e32 v183, v130, v178
	v_fmac_f32_e32 v182, v131, v178
	v_fmac_f32_e32 v181, v132, v178
	v_fmac_f32_e32 v180, v133, v178
	v_fmac_f32_e32 v179, v134, v178
	v_fma_f32 v178, v135, v178, v1
	v_fmac_f32_e32 v191, v121, v177
	v_fmac_f32_e32 v190, v122, v177
	v_fmac_f32_e32 v189, v123, v177
	v_fmac_f32_e32 v188, v124, v177
	v_fmac_f32_e32 v187, v125, v177
	v_fmac_f32_e32 v186, v127, v177
	v_fmac_f32_e32 v185, v129, v177
	v_fmac_f32_e32 v184, v126, v177
	v_fmac_f32_e32 v183, v128, v177
	v_fmac_f32_e32 v182, v130, v177
	v_fmac_f32_e32 v181, v131, v177
	v_fmac_f32_e32 v180, v132, v177
	v_fmac_f32_e32 v179, v133, v177
	v_fmac_f32_e32 v178, v134, v177
	v_fma_f32 v177, v135, v177, v1
	v_fmac_f32_e32 v191, v16, v176
	v_fmac_f32_e32 v190, v121, v176
	v_fmac_f32_e32 v189, v122, v176
	v_fmac_f32_e32 v188, v123, v176
	v_fmac_f32_e32 v187, v124, v176
	v_fmac_f32_e32 v186, v125, v176
	v_fmac_f32_e32 v185, v127, v176
	v_fmac_f32_e32 v184, v129, v176
	v_fmac_f32_e32 v183, v126, v176
	v_fmac_f32_e32 v182, v128, v176
	v_fmac_f32_e32 v181, v130, v176
	v_fmac_f32_e32 v180, v131, v176
	v_fmac_f32_e32 v179, v132, v176
	v_fmac_f32_e32 v178, v133, v176
	v_fmac_f32_e32 v177, v134, v176
	v_fma_f32 v176, v135, v176, v1
	v_fmac_f32_e32 v191, v15, v175
	v_fmac_f32_e32 v190, v16, v175
	v_fmac_f32_e32 v189, v121, v175
	v_fmac_f32_e32 v188, v122, v175
	v_fmac_f32_e32 v187, v123, v175
	v_fmac_f32_e32 v186, v124, v175
	v_fmac_f32_e32 v185, v125, v175
	v_fmac_f32_e32 v184, v127, v175
	v_fmac_f32_e32 v183, v129, v175
	v_fmac_f32_e32 v182, v126, v175
	v_fmac_f32_e32 v181, v128, v175
	v_fmac_f32_e32 v180, v130, v175
	v_fmac_f32_e32 v179, v131, v175
	v_fmac_f32_e32 v178, v132, v175
	v_fmac_f32_e32 v177, v133, v175
	v_fmac_f32_e32 v176, v134, v175
	v_fma_f32 v175, v135, v175, v1
	v_fmac_f32_e32 v191, v14, v174
	v_fmac_f32_e32 v190, v15, v174
	v_fmac_f32_e32 v189, v16, v174
	v_fmac_f32_e32 v188, v121, v174
	v_fmac_f32_e32 v187, v122, v174
	v_fmac_f32_e32 v186, v123, v174
	v_fmac_f32_e32 v185, v124, v174
	v_fmac_f32_e32 v184, v125, v174
	v_fmac_f32_e32 v183, v127, v174
	v_fmac_f32_e32 v182, v129, v174
	v_fmac_f32_e32 v181, v126, v174
	v_fmac_f32_e32 v180, v128, v174
	v_fmac_f32_e32 v179, v130, v174
	v_fmac_f32_e32 v178, v131, v174
	v_fmac_f32_e32 v177, v132, v174
	v_fmac_f32_e32 v176, v133, v174
	v_fmac_f32_e32 v175, v134, v174
	v_fma_f32 v174, v135, v174, v1
	v_fmac_f32_e32 v191, v13, v173
	v_fmac_f32_e32 v190, v14, v173
	v_fmac_f32_e32 v189, v15, v173
	v_fmac_f32_e32 v188, v16, v173
	v_fmac_f32_e32 v187, v121, v173
	v_fmac_f32_e32 v186, v122, v173
	v_fmac_f32_e32 v185, v123, v173
	v_fmac_f32_e32 v184, v124, v173
	v_fmac_f32_e32 v183, v125, v173
	v_fmac_f32_e32 v182, v127, v173
	v_fmac_f32_e32 v181, v129, v173
	v_fmac_f32_e32 v180, v126, v173
	v_fmac_f32_e32 v179, v128, v173
	v_fmac_f32_e32 v178, v130, v173
	v_fmac_f32_e32 v177, v131, v173
	v_fmac_f32_e32 v176, v132, v173
	v_fmac_f32_e32 v175, v133, v173
	v_fmac_f32_e32 v174, v134, v173
	v_fma_f32 v173, v135, v173, v1
	v_fmac_f32_e32 v191, v12, v172
	v_fmac_f32_e32 v190, v13, v172
	v_fmac_f32_e32 v189, v14, v172
	v_fmac_f32_e32 v188, v15, v172
	v_fmac_f32_e32 v187, v16, v172
	v_fmac_f32_e32 v186, v121, v172
	v_fmac_f32_e32 v185, v122, v172
	v_fmac_f32_e32 v184, v123, v172
	v_fmac_f32_e32 v183, v124, v172
	v_fmac_f32_e32 v182, v125, v172
	v_fmac_f32_e32 v181, v127, v172
	v_fmac_f32_e32 v180, v129, v172
	v_fmac_f32_e32 v179, v126, v172
	v_fmac_f32_e32 v178, v128, v172
	v_fmac_f32_e32 v177, v130, v172
	v_fmac_f32_e32 v176, v131, v172
	v_fmac_f32_e32 v175, v132, v172
	v_fmac_f32_e32 v174, v133, v172
	v_fmac_f32_e32 v173, v134, v172
	v_fma_f32 v172, v135, v172, v1
	v_fmac_f32_e32 v191, v11, v171
	v_fmac_f32_e32 v190, v12, v171
	v_fmac_f32_e32 v189, v13, v171
	v_fmac_f32_e32 v188, v14, v171
	v_fmac_f32_e32 v187, v15, v171
	v_fmac_f32_e32 v186, v16, v171
	v_fmac_f32_e32 v185, v121, v171
	v_fmac_f32_e32 v184, v122, v171
	v_fmac_f32_e32 v183, v123, v171
	v_fmac_f32_e32 v182, v124, v171
	v_fmac_f32_e32 v181, v125, v171
	v_fmac_f32_e32 v180, v127, v171
	v_fmac_f32_e32 v179, v129, v171
	v_fmac_f32_e32 v178, v126, v171
	v_fmac_f32_e32 v177, v128, v171
	v_fmac_f32_e32 v176, v130, v171
	v_fmac_f32_e32 v175, v131, v171
	v_fmac_f32_e32 v174, v132, v171
	v_fmac_f32_e32 v173, v133, v171
	v_fmac_f32_e32 v172, v134, v171
	v_fma_f32 v171, v135, v171, v1
	v_fmac_f32_e32 v191, v10, v170
	v_fmac_f32_e32 v190, v11, v170
	v_fmac_f32_e32 v189, v12, v170
	v_fmac_f32_e32 v188, v13, v170
	v_fmac_f32_e32 v187, v14, v170
	v_fmac_f32_e32 v186, v15, v170
	v_fmac_f32_e32 v185, v16, v170
	v_fmac_f32_e32 v184, v121, v170
	v_fmac_f32_e32 v183, v122, v170
	v_fmac_f32_e32 v182, v123, v170
	v_fmac_f32_e32 v181, v124, v170
	v_fmac_f32_e32 v180, v125, v170
	v_fmac_f32_e32 v179, v127, v170
	v_fmac_f32_e32 v178, v129, v170
	v_fmac_f32_e32 v177, v126, v170
	v_fmac_f32_e32 v176, v128, v170
	v_fmac_f32_e32 v175, v130, v170
	v_fmac_f32_e32 v174, v131, v170
	v_fmac_f32_e32 v173, v132, v170
	v_fmac_f32_e32 v172, v133, v170
	v_fmac_f32_e32 v171, v134, v170
	v_fma_f32 v170, v135, v170, v1
	v_fmac_f32_e32 v191, v9, v169
	v_fmac_f32_e32 v190, v10, v169
	v_fmac_f32_e32 v189, v11, v169
	v_fmac_f32_e32 v188, v12, v169
	v_fmac_f32_e32 v187, v13, v169
	v_fmac_f32_e32 v186, v14, v169
	v_fmac_f32_e32 v185, v15, v169
	v_fmac_f32_e32 v184, v16, v169
	v_fmac_f32_e32 v183, v121, v169
	v_fmac_f32_e32 v182, v122, v169
	v_fmac_f32_e32 v181, v123, v169
	v_fmac_f32_e32 v180, v124, v169
	v_fmac_f32_e32 v179, v125, v169
	v_fmac_f32_e32 v178, v127, v169
	v_fmac_f32_e32 v177, v129, v169
	v_fmac_f32_e32 v176, v126, v169
	v_fmac_f32_e32 v175, v128, v169
	v_fmac_f32_e32 v174, v130, v169
	v_fmac_f32_e32 v173, v131, v169
	v_fmac_f32_e32 v172, v132, v169
	v_fmac_f32_e32 v171, v133, v169
	v_fmac_f32_e32 v170, v134, v169
	v_fma_f32 v169, v135, v169, v1
	v_fmac_f32_e32 v191, v8, v168
	v_fmac_f32_e32 v190, v9, v168
	v_fmac_f32_e32 v189, v10, v168
	v_fmac_f32_e32 v188, v11, v168
	v_fmac_f32_e32 v187, v12, v168
	v_fmac_f32_e32 v186, v13, v168
	v_fmac_f32_e32 v185, v14, v168
	v_fmac_f32_e32 v184, v15, v168
	v_fmac_f32_e32 v183, v16, v168
	v_fmac_f32_e32 v182, v121, v168
	v_fmac_f32_e32 v181, v122, v168
	v_fmac_f32_e32 v180, v123, v168
	v_fmac_f32_e32 v179, v124, v168
	v_fmac_f32_e32 v178, v125, v168
	v_fmac_f32_e32 v177, v127, v168
	v_fmac_f32_e32 v176, v129, v168
	v_fmac_f32_e32 v175, v126, v168
	v_fmac_f32_e32 v174, v128, v168
	v_fmac_f32_e32 v173, v130, v168
	v_fmac_f32_e32 v172, v131, v168
	v_fmac_f32_e32 v171, v132, v168
	v_fmac_f32_e32 v170, v133, v168
	v_fmac_f32_e32 v169, v134, v168
	v_fma_f32 v168, v135, v168, v1
	v_fmac_f32_e32 v191, v7, v167
	v_fmac_f32_e32 v190, v8, v167
	v_fmac_f32_e32 v189, v9, v167
	v_fmac_f32_e32 v188, v10, v167
	v_fmac_f32_e32 v187, v11, v167
	v_fmac_f32_e32 v186, v12, v167
	v_fmac_f32_e32 v185, v13, v167
	v_fmac_f32_e32 v184, v14, v167
	v_fmac_f32_e32 v183, v15, v167
	v_fmac_f32_e32 v182, v16, v167
	v_fmac_f32_e32 v181, v121, v167
	v_fmac_f32_e32 v180, v122, v167
	v_fmac_f32_e32 v179, v123, v167
	v_fmac_f32_e32 v178, v124, v167
	v_fmac_f32_e32 v177, v125, v167
	v_fmac_f32_e32 v176, v127, v167
	v_fmac_f32_e32 v175, v129, v167
	v_fmac_f32_e32 v174, v126, v167
	v_fmac_f32_e32 v173, v128, v167
	v_fmac_f32_e32 v172, v130, v167
	v_fmac_f32_e32 v171, v131, v167
	v_fmac_f32_e32 v170, v132, v167
	v_fmac_f32_e32 v169, v133, v167
	v_fmac_f32_e32 v168, v134, v167
	v_fma_f32 v167, v135, v167, v1
	v_fmac_f32_e32 v1, v135, v142
	v_fmac_f32_e32 v167, v134, v142
	v_fmac_f32_e32 v1, v134, v164
	v_fmac_f32_e32 v168, v133, v142
	v_fmac_f32_e32 v167, v133, v164
	v_fmac_f32_e32 v1, v133, v161
	v_fmac_f32_e32 v169, v132, v142
	v_fmac_f32_e32 v168, v132, v164
	v_fmac_f32_e32 v167, v132, v161
	v_fmac_f32_e32 v1, v132, v158
	v_fmac_f32_e32 v170, v131, v142
	v_fmac_f32_e32 v169, v131, v164
	v_fmac_f32_e32 v168, v131, v161
	v_fmac_f32_e32 v167, v131, v158
	v_fmac_f32_e32 v1, v131, v155
	v_fmac_f32_e32 v171, v130, v142
	v_fmac_f32_e32 v170, v130, v164
	v_fmac_f32_e32 v169, v130, v161
	v_fmac_f32_e32 v168, v130, v158
	v_fmac_f32_e32 v167, v130, v155
	v_fmac_f32_e32 v1, v130, v152
	v_fmac_f32_e32 v172, v128, v142
	v_fmac_f32_e32 v171, v128, v164
	v_fmac_f32_e32 v170, v128, v161
	v_fmac_f32_e32 v169, v128, v158
	v_fmac_f32_e32 v168, v128, v155
	v_fmac_f32_e32 v167, v128, v152
	v_fmac_f32_e32 v1, v128, v149
	v_fmac_f32_e32 v173, v126, v142
	v_fmac_f32_e32 v172, v126, v164
	v_fmac_f32_e32 v171, v126, v161
	v_fmac_f32_e32 v170, v126, v158
	v_fmac_f32_e32 v169, v126, v155
	v_fmac_f32_e32 v168, v126, v152
	v_fmac_f32_e32 v167, v126, v149
	v_fmac_f32_e32 v1, v126, v146
	v_fmac_f32_e32 v174, v129, v142
	v_fmac_f32_e32 v173, v129, v164
	v_fmac_f32_e32 v172, v129, v161
	v_fmac_f32_e32 v171, v129, v158
	v_fmac_f32_e32 v170, v129, v155
	v_fmac_f32_e32 v169, v129, v152
	v_fmac_f32_e32 v168, v129, v149
	v_fmac_f32_e32 v167, v129, v146
	v_fmac_f32_e32 v1, v129, v143
	v_fmac_f32_e32 v175, v127, v142
	v_fmac_f32_e32 v174, v127, v164
	v_fmac_f32_e32 v173, v127, v161
	v_fmac_f32_e32 v172, v127, v158
	v_fmac_f32_e32 v171, v127, v155
	v_fmac_f32_e32 v170, v127, v152
	v_fmac_f32_e32 v169, v127, v149
	v_fmac_f32_e32 v168, v127, v146
	v_fmac_f32_e32 v167, v127, v143
	v_fmac_f32_e32 v1, v127, v165
	v_fmac_f32_e32 v176, v125, v142
	v_fmac_f32_e32 v175, v125, v164
	v_fmac_f32_e32 v174, v125, v161
	v_fmac_f32_e32 v173, v125, v158
	v_fmac_f32_e32 v172, v125, v155
	v_fmac_f32_e32 v171, v125, v152
	v_fmac_f32_e32 v170, v125, v149
	v_fmac_f32_e32 v169, v125, v146
	v_fmac_f32_e32 v168, v125, v143
	v_fmac_f32_e32 v167, v125, v165
	v_fmac_f32_e32 v1, v125, v162
	v_fmac_f32_e32 v177, v124, v142
	v_fmac_f32_e32 v176, v124, v164
	v_fmac_f32_e32 v175, v124, v161
	v_fmac_f32_e32 v174, v124, v158
	v_fmac_f32_e32 v173, v124, v155
	v_fmac_f32_e32 v172, v124, v152
	v_fmac_f32_e32 v171, v124, v149
	v_fmac_f32_e32 v170, v124, v146
	v_fmac_f32_e32 v169, v124, v143
	v_fmac_f32_e32 v168, v124, v165
	v_fmac_f32_e32 v167, v124, v162
	v_fmac_f32_e32 v1, v124, v159
	v_fmac_f32_e32 v178, v123, v142
	v_fmac_f32_e32 v177, v123, v164
	v_fmac_f32_e32 v176, v123, v161
	v_fmac_f32_e32 v175, v123, v158
	v_fmac_f32_e32 v174, v123, v155
	v_fmac_f32_e32 v173, v123, v152
	v_fmac_f32_e32 v172, v123, v149
	v_fmac_f32_e32 v171, v123, v146
	v_fmac_f32_e32 v170, v123, v143
	v_fmac_f32_e32 v169, v123, v165
	v_fmac_f32_e32 v168, v123, v162
	v_fmac_f32_e32 v167, v123, v159
	v_fmac_f32_e32 v1, v123, v156
	v_fmac_f32_e32 v179, v122, v142
	v_fmac_f32_e32 v178, v122, v164
	v_fmac_f32_e32 v177, v122, v161
	v_fmac_f32_e32 v176, v122, v158
	v_fmac_f32_e32 v175, v122, v155
	v_fmac_f32_e32 v174, v122, v152
	v_fmac_f32_e32 v173, v122, v149
	v_fmac_f32_e32 v172, v122, v146
	v_fmac_f32_e32 v171, v122, v143
	v_fmac_f32_e32 v170, v122, v165
	v_fmac_f32_e32 v169, v122, v162
	v_fmac_f32_e32 v168, v122, v159
	v_fmac_f32_e32 v167, v122, v156
	v_fmac_f32_e32 v1, v122, v153
	v_fmac_f32_e32 v180, v121, v142
	v_fmac_f32_e32 v179, v121, v164
	v_fmac_f32_e32 v178, v121, v161
	v_fmac_f32_e32 v177, v121, v158
	v_fmac_f32_e32 v176, v121, v155
	v_fmac_f32_e32 v175, v121, v152
	v_fmac_f32_e32 v174, v121, v149
	v_fmac_f32_e32 v173, v121, v146
	v_fmac_f32_e32 v172, v121, v143
	v_fmac_f32_e32 v171, v121, v165
	v_fmac_f32_e32 v170, v121, v162
	v_fmac_f32_e32 v169, v121, v159
	v_fmac_f32_e32 v168, v121, v156
	v_fmac_f32_e32 v167, v121, v153
	v_fmac_f32_e32 v1, v121, v150
	v_fmac_f32_e32 v181, v16, v142
	v_fmac_f32_e32 v180, v16, v164
	v_fmac_f32_e32 v179, v16, v161
	v_fmac_f32_e32 v178, v16, v158
	v_fmac_f32_e32 v177, v16, v155
	v_fmac_f32_e32 v176, v16, v152
	v_fmac_f32_e32 v175, v16, v149
	v_fmac_f32_e32 v174, v16, v146
	v_fmac_f32_e32 v173, v16, v143
	v_fmac_f32_e32 v172, v16, v165
	v_fmac_f32_e32 v171, v16, v162
	v_fmac_f32_e32 v170, v16, v159
	v_fmac_f32_e32 v169, v16, v156
	v_fmac_f32_e32 v168, v16, v153
	v_fmac_f32_e32 v167, v16, v150
	v_fmac_f32_e32 v1, v16, v147
	v_fmac_f32_e32 v182, v15, v142
	v_fmac_f32_e32 v181, v15, v164
	v_fmac_f32_e32 v180, v15, v161
	v_fmac_f32_e32 v179, v15, v158
	v_fmac_f32_e32 v178, v15, v155
	v_fmac_f32_e32 v177, v15, v152
	v_fmac_f32_e32 v176, v15, v149
	v_fmac_f32_e32 v175, v15, v146
	v_fmac_f32_e32 v174, v15, v143
	v_fmac_f32_e32 v173, v15, v165
	v_fmac_f32_e32 v172, v15, v162
	v_fmac_f32_e32 v171, v15, v159
	v_fmac_f32_e32 v170, v15, v156
	v_fmac_f32_e32 v169, v15, v153
	v_fmac_f32_e32 v168, v15, v150
	v_fmac_f32_e32 v167, v15, v147
	v_fmac_f32_e32 v1, v15, v144
	v_fmac_f32_e32 v183, v14, v142
	v_fmac_f32_e32 v182, v14, v164
	v_fmac_f32_e32 v181, v14, v161
	v_fmac_f32_e32 v180, v14, v158
	v_fmac_f32_e32 v179, v14, v155
	v_fmac_f32_e32 v178, v14, v152
	v_fmac_f32_e32 v177, v14, v149
	v_fmac_f32_e32 v176, v14, v146
	v_fmac_f32_e32 v175, v14, v143
	v_fmac_f32_e32 v174, v14, v165
	v_fmac_f32_e32 v173, v14, v162
	v_fmac_f32_e32 v172, v14, v159
	v_fmac_f32_e32 v171, v14, v156
	v_fmac_f32_e32 v170, v14, v153
	v_fmac_f32_e32 v169, v14, v150
	v_fmac_f32_e32 v168, v14, v147
	v_fmac_f32_e32 v167, v14, v144
	v_fmac_f32_e32 v1, v14, v166
	v_fmac_f32_e32 v184, v13, v142
	v_fmac_f32_e32 v183, v13, v164
	v_fmac_f32_e32 v182, v13, v161
	v_fmac_f32_e32 v181, v13, v158
	v_fmac_f32_e32 v180, v13, v155
	v_fmac_f32_e32 v179, v13, v152
	v_fmac_f32_e32 v178, v13, v149
	v_fmac_f32_e32 v177, v13, v146
	v_fmac_f32_e32 v176, v13, v143
	v_fmac_f32_e32 v175, v13, v165
	v_fmac_f32_e32 v174, v13, v162
	v_fmac_f32_e32 v173, v13, v159
	v_fmac_f32_e32 v172, v13, v156
	v_fmac_f32_e32 v171, v13, v153
	v_fmac_f32_e32 v170, v13, v150
	v_fmac_f32_e32 v169, v13, v147
	v_fmac_f32_e32 v168, v13, v144
	v_fmac_f32_e32 v167, v13, v166
	v_fmac_f32_e32 v1, v13, v163
	v_fmac_f32_e32 v185, v12, v142
	v_fmac_f32_e32 v184, v12, v164
	v_fmac_f32_e32 v183, v12, v161
	v_fmac_f32_e32 v182, v12, v158
	v_fmac_f32_e32 v181, v12, v155
	v_fmac_f32_e32 v180, v12, v152
	v_fmac_f32_e32 v179, v12, v149
	v_fmac_f32_e32 v178, v12, v146
	v_fmac_f32_e32 v177, v12, v143
	v_fmac_f32_e32 v176, v12, v165
	v_fmac_f32_e32 v175, v12, v162
	v_fmac_f32_e32 v174, v12, v159
	v_fmac_f32_e32 v173, v12, v156
	v_fmac_f32_e32 v172, v12, v153
	v_fmac_f32_e32 v171, v12, v150
	v_fmac_f32_e32 v170, v12, v147
	v_fmac_f32_e32 v169, v12, v144
	v_fmac_f32_e32 v168, v12, v166
	v_fmac_f32_e32 v167, v12, v163
	v_fmac_f32_e32 v1, v12, v160
	v_fmac_f32_e32 v186, v11, v142
	v_fmac_f32_e32 v185, v11, v164
	v_fmac_f32_e32 v184, v11, v161
	v_fmac_f32_e32 v183, v11, v158
	v_fmac_f32_e32 v182, v11, v155
	v_fmac_f32_e32 v181, v11, v152
	v_fmac_f32_e32 v180, v11, v149
	v_fmac_f32_e32 v179, v11, v146
	v_fmac_f32_e32 v178, v11, v143
	v_fmac_f32_e32 v177, v11, v165
	v_fmac_f32_e32 v176, v11, v162
	v_fmac_f32_e32 v175, v11, v159
	v_fmac_f32_e32 v174, v11, v156
	v_fmac_f32_e32 v173, v11, v153
	v_fmac_f32_e32 v172, v11, v150
	v_fmac_f32_e32 v171, v11, v147
	v_fmac_f32_e32 v170, v11, v144
	v_fmac_f32_e32 v169, v11, v166
	v_fmac_f32_e32 v168, v11, v163
	v_fmac_f32_e32 v167, v11, v160
	v_fmac_f32_e32 v1, v11, v157
	v_fmac_f32_e32 v187, v10, v142
	v_fmac_f32_e32 v186, v10, v164
	v_fmac_f32_e32 v185, v10, v161
	v_fmac_f32_e32 v184, v10, v158
	v_fmac_f32_e32 v183, v10, v155
	v_fmac_f32_e32 v182, v10, v152
	v_fmac_f32_e32 v181, v10, v149
	v_fmac_f32_e32 v180, v10, v146
	v_fmac_f32_e32 v179, v10, v143
	v_fmac_f32_e32 v178, v10, v165
	v_fmac_f32_e32 v177, v10, v162
	v_fmac_f32_e32 v176, v10, v159
	v_fmac_f32_e32 v175, v10, v156
	v_fmac_f32_e32 v174, v10, v153
	v_fmac_f32_e32 v173, v10, v150
	v_fmac_f32_e32 v172, v10, v147
	v_fmac_f32_e32 v171, v10, v144
	v_fmac_f32_e32 v170, v10, v166
	v_fmac_f32_e32 v169, v10, v163
	v_fmac_f32_e32 v168, v10, v160
	v_fmac_f32_e32 v167, v10, v157
	v_fmac_f32_e32 v1, v10, v154
	v_fmac_f32_e32 v188, v9, v142
	v_fmac_f32_e32 v187, v9, v164
	v_fmac_f32_e32 v186, v9, v161
	v_fmac_f32_e32 v185, v9, v158
	v_fmac_f32_e32 v184, v9, v155
	v_fmac_f32_e32 v183, v9, v152
	v_fmac_f32_e32 v182, v9, v149
	v_fmac_f32_e32 v181, v9, v146
	v_fmac_f32_e32 v180, v9, v143
	v_fmac_f32_e32 v179, v9, v165
	v_fmac_f32_e32 v178, v9, v162
	v_fmac_f32_e32 v177, v9, v159
	v_fmac_f32_e32 v176, v9, v156
	v_fmac_f32_e32 v175, v9, v153
	v_fmac_f32_e32 v174, v9, v150
	v_fmac_f32_e32 v173, v9, v147
	v_fmac_f32_e32 v172, v9, v144
	v_fmac_f32_e32 v171, v9, v166
	v_fmac_f32_e32 v170, v9, v163
	v_fmac_f32_e32 v169, v9, v160
	v_fmac_f32_e32 v168, v9, v157
	v_fmac_f32_e32 v167, v9, v154
	v_fmac_f32_e32 v1, v9, v151
	v_fmac_f32_e32 v189, v8, v142
	v_fmac_f32_e32 v188, v8, v164
	v_fmac_f32_e32 v187, v8, v161
	v_fmac_f32_e32 v186, v8, v158
	v_fmac_f32_e32 v185, v8, v155
	v_fmac_f32_e32 v184, v8, v152
	v_fmac_f32_e32 v183, v8, v149
	v_fmac_f32_e32 v182, v8, v146
	v_fmac_f32_e32 v181, v8, v143
	v_fmac_f32_e32 v180, v8, v165
	v_fmac_f32_e32 v179, v8, v162
	v_fmac_f32_e32 v178, v8, v159
	v_fmac_f32_e32 v177, v8, v156
	v_fmac_f32_e32 v176, v8, v153
	v_fmac_f32_e32 v175, v8, v150
	v_fmac_f32_e32 v174, v8, v147
	v_fmac_f32_e32 v173, v8, v144
	v_fmac_f32_e32 v172, v8, v166
	v_fmac_f32_e32 v171, v8, v163
	v_fmac_f32_e32 v170, v8, v160
	v_fmac_f32_e32 v169, v8, v157
	v_fmac_f32_e32 v168, v8, v154
	v_fmac_f32_e32 v167, v8, v151
	v_fmac_f32_e32 v1, v8, v148
	v_fmac_f32_e32 v190, v7, v142
	v_fmac_f32_e32 v189, v7, v164
	v_fmac_f32_e32 v188, v7, v161
	v_fmac_f32_e32 v187, v7, v158
	v_fmac_f32_e32 v186, v7, v155
	v_fmac_f32_e32 v185, v7, v152
	v_fmac_f32_e32 v184, v7, v149
	v_fmac_f32_e32 v183, v7, v146
	v_fmac_f32_e32 v182, v7, v143
	v_fmac_f32_e32 v181, v7, v165
	v_fmac_f32_e32 v180, v7, v162
	v_fmac_f32_e32 v179, v7, v159
	v_fmac_f32_e32 v178, v7, v156
	v_fmac_f32_e32 v177, v7, v153
	v_fmac_f32_e32 v176, v7, v150
	v_fmac_f32_e32 v175, v7, v147
	v_fmac_f32_e32 v174, v7, v144
	v_fmac_f32_e32 v173, v7, v166
	v_fmac_f32_e32 v172, v7, v163
	v_fmac_f32_e32 v171, v7, v160
	v_fmac_f32_e32 v170, v7, v157
	v_fmac_f32_e32 v169, v7, v154
	v_fmac_f32_e32 v168, v7, v151
	v_fmac_f32_e32 v167, v7, v148
	v_fmac_f32_e32 v1, v7, v145
	v_fmac_f32_e32 v191, v6, v142
	v_fmac_f32_e32 v190, v6, v164
	v_fmac_f32_e32 v189, v6, v161
	v_fmac_f32_e32 v188, v6, v158
	v_fmac_f32_e32 v187, v6, v155
	v_fmac_f32_e32 v186, v6, v152
	v_fmac_f32_e32 v185, v6, v149
	v_fmac_f32_e32 v184, v6, v146
	v_fmac_f32_e32 v183, v6, v143
	v_fmac_f32_e32 v182, v6, v165
	v_fmac_f32_e32 v181, v6, v162
	v_fmac_f32_e32 v180, v6, v159
	v_fmac_f32_e32 v179, v6, v156
	v_fmac_f32_e32 v178, v6, v153
	v_fmac_f32_e32 v177, v6, v150
	v_fmac_f32_e32 v176, v6, v147
	v_fmac_f32_e32 v175, v6, v144
	v_fmac_f32_e32 v174, v6, v166
	v_fmac_f32_e32 v173, v6, v163
	v_fmac_f32_e32 v172, v6, v160
	v_fmac_f32_e32 v171, v6, v157
	v_fmac_f32_e32 v170, v6, v154
	v_fmac_f32_e32 v169, v6, v151
	v_fmac_f32_e32 v168, v6, v148
	v_fmac_f32_e32 v167, v6, v145
	v_fmac_f32_e32 v1, v6, v141
	v_fmac_f32_e32 v191, v5, v164
	v_fmac_f32_e32 v190, v5, v161
	v_fmac_f32_e32 v189, v5, v158
	v_fmac_f32_e32 v188, v5, v155
	v_fmac_f32_e32 v187, v5, v152
	v_fmac_f32_e32 v186, v5, v149
	v_fmac_f32_e32 v185, v5, v146
	v_fmac_f32_e32 v184, v5, v143
	v_fmac_f32_e32 v183, v5, v165
	v_fmac_f32_e32 v182, v5, v162
	v_fmac_f32_e32 v181, v5, v159
	v_fmac_f32_e32 v180, v5, v156
	v_fmac_f32_e32 v179, v5, v153
	v_fmac_f32_e32 v178, v5, v150
	v_fmac_f32_e32 v177, v5, v147
	v_fmac_f32_e32 v176, v5, v144
	v_fmac_f32_e32 v175, v5, v166
	v_fmac_f32_e32 v174, v5, v163
	v_fmac_f32_e32 v173, v5, v160
	v_fmac_f32_e32 v172, v5, v157
	v_fmac_f32_e32 v171, v5, v154
	v_fmac_f32_e32 v170, v5, v151
	v_fmac_f32_e32 v169, v5, v148
	v_fmac_f32_e32 v168, v5, v145
	v_fmac_f32_e32 v167, v5, v141
	v_fmac_f32_e32 v1, v5, v140
	v_fmac_f32_e32 v191, v4, v161
	v_fmac_f32_e32 v190, v4, v158
	v_fmac_f32_e32 v189, v4, v155
	v_fmac_f32_e32 v188, v4, v152
	v_fmac_f32_e32 v187, v4, v149
	v_fmac_f32_e32 v186, v4, v146
	v_fmac_f32_e32 v185, v4, v143
	v_fmac_f32_e32 v184, v4, v165
	v_fmac_f32_e32 v183, v4, v162
	v_fmac_f32_e32 v182, v4, v159
	v_fmac_f32_e32 v181, v4, v156
	v_fmac_f32_e32 v180, v4, v153
	v_fmac_f32_e32 v179, v4, v150
	v_fmac_f32_e32 v178, v4, v147
	v_fmac_f32_e32 v177, v4, v144
	v_fmac_f32_e32 v176, v4, v166
	v_fmac_f32_e32 v175, v4, v163
	v_fmac_f32_e32 v174, v4, v160
	v_fmac_f32_e32 v173, v4, v157
	v_fmac_f32_e32 v172, v4, v154
	v_fmac_f32_e32 v171, v4, v151
	v_fmac_f32_e32 v170, v4, v148
	v_fmac_f32_e32 v169, v4, v145
	v_fmac_f32_e32 v168, v4, v141
	v_fmac_f32_e32 v167, v4, v140
	v_fmac_f32_e32 v1, v4, v139
	v_fmac_f32_e32 v191, v3, v158
	v_fmac_f32_e32 v190, v3, v155
	v_fmac_f32_e32 v189, v3, v152
	v_fmac_f32_e32 v188, v3, v149
	v_fmac_f32_e32 v187, v3, v146
	v_fmac_f32_e32 v186, v3, v143
	v_fmac_f32_e32 v185, v3, v165
	v_fmac_f32_e32 v184, v3, v162
	v_fmac_f32_e32 v183, v3, v159
	v_fmac_f32_e32 v182, v3, v156
	v_fmac_f32_e32 v181, v3, v153
	v_fmac_f32_e32 v180, v3, v150
	v_fmac_f32_e32 v179, v3, v147
	v_fmac_f32_e32 v178, v3, v144
	v_fmac_f32_e32 v177, v3, v166
	v_fmac_f32_e32 v176, v3, v163
	v_fmac_f32_e32 v175, v3, v160
	v_fmac_f32_e32 v174, v3, v157
	v_fmac_f32_e32 v173, v3, v154
	v_fmac_f32_e32 v172, v3, v151
	v_fmac_f32_e32 v171, v3, v148
	v_fmac_f32_e32 v170, v3, v145
	v_fmac_f32_e32 v169, v3, v141
	v_fmac_f32_e32 v168, v3, v140
	v_fmac_f32_e32 v167, v3, v139
	v_fmac_f32_e32 v1, v3, v138
	v_fmac_f32_e32 v191, v2, v155
	v_fmac_f32_e32 v190, v2, v152
	v_fmac_f32_e32 v189, v2, v149
	v_fmac_f32_e32 v188, v2, v146
	v_fmac_f32_e32 v187, v2, v143
	v_fmac_f32_e32 v186, v2, v165
	v_fmac_f32_e32 v185, v2, v162
	v_fmac_f32_e32 v184, v2, v159
	v_fmac_f32_e32 v183, v2, v156
	v_fmac_f32_e32 v182, v2, v153
	v_fmac_f32_e32 v181, v2, v150
	v_fmac_f32_e32 v180, v2, v147
	v_fmac_f32_e32 v179, v2, v144
	v_fmac_f32_e32 v178, v2, v166
	v_fmac_f32_e32 v177, v2, v163
	v_fmac_f32_e32 v176, v2, v160
	v_fmac_f32_e32 v175, v2, v157
	v_fmac_f32_e32 v174, v2, v154
	v_fmac_f32_e32 v173, v2, v151
	v_fmac_f32_e32 v172, v2, v148
	v_fmac_f32_e32 v171, v2, v145
	v_fmac_f32_e32 v170, v2, v141
	v_fmac_f32_e32 v169, v2, v140
	v_fmac_f32_e32 v168, v2, v139
	v_fmac_f32_e32 v167, v2, v138
	v_fmac_f32_e32 v1, v2, v137
	v_fmac_f32_e32 v191, v0, v152
	v_fmac_f32_e32 v190, v0, v149
	v_fmac_f32_e32 v189, v0, v146
	v_fmac_f32_e32 v188, v0, v143
	v_fmac_f32_e32 v187, v0, v165
	v_fmac_f32_e32 v186, v0, v162
	v_fmac_f32_e32 v185, v0, v159
	v_fmac_f32_e32 v184, v0, v156
	v_fmac_f32_e32 v183, v0, v153
	v_fmac_f32_e32 v182, v0, v150
	v_fmac_f32_e32 v181, v0, v147
	v_fmac_f32_e32 v180, v0, v144
	v_fmac_f32_e32 v179, v0, v166
	v_fmac_f32_e32 v178, v0, v163
	v_fmac_f32_e32 v177, v0, v160
	v_fmac_f32_e32 v176, v0, v157
	v_fmac_f32_e32 v175, v0, v154
	v_fmac_f32_e32 v174, v0, v151
	v_fmac_f32_e32 v173, v0, v148
	v_fmac_f32_e32 v172, v0, v145
	v_fmac_f32_e32 v171, v0, v141
	v_fmac_f32_e32 v170, v0, v140
	v_fmac_f32_e32 v169, v0, v139
	v_fmac_f32_e32 v168, v0, v138
	v_fmac_f32_e32 v167, v0, v137
	v_fmac_f32_e32 v1, v0, v136
	ds_write2st64_b32 v116, v191, v190 offset0:48 offset1:56
	ds_write2st64_b32 v116, v189, v188 offset0:64 offset1:72
	ds_write2st64_b32 v116, v187, v186 offset0:80 offset1:88
	ds_write2st64_b32 v116, v185, v184 offset0:96 offset1:104
	ds_write2st64_b32 v116, v183, v182 offset0:112 offset1:120
	ds_write2st64_b32 v116, v181, v180 offset0:128 offset1:136
	ds_write2st64_b32 v116, v179, v178 offset0:144 offset1:152
	ds_write2st64_b32 v116, v177, v176 offset0:160 offset1:168
	ds_write2st64_b32 v116, v175, v174 offset0:176 offset1:184
	ds_write2st64_b32 v116, v173, v172 offset0:192 offset1:200
	ds_write2st64_b32 v116, v171, v170 offset0:208 offset1:216
	ds_write2st64_b32 v116, v169, v168 offset0:224 offset1:232
	ds_write2st64_b32 v116, v167, v1 offset0:240 offset1:248
